# attention unit prologue: second K/V tile loaded together with the first (into free registers) instead of after the first QK^T
# speedup vs baseline: 1.0025x; 1.0012x over previous
; __device__ __forceinline__ int v_st(int k, int c) { const int kk = (k & ~0xC) | ((k & 4) << 1) | ((k & 8) >> 1); return ((kk >> 3) * 4 + (c >> 5)) * 512 + ((kk & 7) * 32 + (c & 31)) * 2; }
; __device__ __forceinline__ int v_rd_base(int lane) { return ((lane & 3) << 3) | (((lane >> 2) & 3) << 6) | (((lane >> 4) & 1) << 5) | (((lane >> 5) & 1) << 8); }
; #define SLOAD(i, k0) do { const char* vt_ = (const char*)Vh + (size_t)(k0) * 256; const char* kt_ = (const char*)Kh + (size_t)(k0) * 128; \
;     sr_[i].vs0 = *reinterpret_cast<const bf16x8*>(vt_ + voff0); sr_[i].vs1 = *reinterpret_cast<const bf16x8*>(vt_ + 32 * 256 + voff0); \
;     sr_[i].ks0 = *reinterpret_cast<const bf16x8*>(kt_ + koff0); } while (0)
; #define SWRITE(b, i) do { *(bf16x8*)(V_lds + (b) * SHM_V + vst0) = sr_[i].vs0; *(bf16x8*)(V_lds + (b) * SHM_V + vst1) = sr_[i].vs1; \
;     *(bf16x8*)(K_lds + (b) * SHM_K + kst) = sr_[i].ks0; } while (0)
; __device__ __forceinline__ void attn_unit(const bf16* __restrict__ Qb, const bf16* __restrict__ Kh, const bf16* __restrict__ Vh, bf16* __restrict__ Ob, int seq, char* lds) {
;     ...
;     const bf16* Qw = Qb + (long)(wid * QBLK + r32) * 64 + hi * 8;
; #pragma unroll
;     for (int d0 = 0; d0 < 4; ++d0) qr[d0] = *reinterpret_cast<const bf16x8*>(Qw + d0 * 16);
;     const int sr = tid >> 4, sc = (tid & 15) * 8, vst0 = v_st(sr, sc), vst1 = v_st(32 + sr, sc);
;     const int kr = tid >> 3, kc = (tid & 7) * 8, kst = KSWZ64(kr, kc * 2);
;     const int vb0 = (int)(uintptr_t)V_lds + v_rd_base(lane);
;     struct { bf16x8 vs0, vs1, ks0; } sr_[1];
;     const unsigned voff0 = (unsigned)((sr * 128 + sc) * 2), koff0 = (unsigned)((kr * 64 + kc) * 2);
;     ...
;     f32x16 pA0, pA1, pB0, pB1; bf16x8 pa0, pa1, pa2, pa3; const int NT = seq / KVBLK;
;     constexpr int SE = 0, SO = 0;
;     SLOAD(SE, 0); asm volatile("s_waitcnt vmcnt(0)" ::: "memory"); SWRITE(0, SE); __syncthreads();
.LBB0_530:
	s_and_b32 s6, s49, 7
	s_and_b32 s58, s50, 7
	s_lshl_b32 s51, s6, 3
	s_lshl_b32 s52, s6, 2
	s_ashr_i32 s53, s50, 6
	s_lshl_b32 s6, s58, 3
	s_add_i32 s10, s6, s53
	s_ashr_i32 s11, s10, 31
	s_lshl_b64 s[6:7], s[10:11], 11
	s_lshl_b32 s11, s50, 5
	s_and_b32 s11, s11, 0x700
	s_or_b32 s6, s6, s11
	s_lshl_b64 s[12:13], s[6:7], 7
	s_add_u32 s12, s3, s12
	s_addc_u32 s13, s14, s13
	s_mul_hi_i32 s11, s10, 0x48000
	s_mul_i32 s10, s10, 0x48000
	s_add_u32 s10, s15, s10
	s_addc_u32 s11, s16, s11
	s_lshl_b32 s59, s58, 2
	s_ashr_i32 s58, s50, 7
	v_mov_b32_e32 v143, v0
	s_add_i32 s59, s59, s58
	s_mul_hi_i32 s65, s59, 0x90000
	v_lshlrev_b32_e32 v17, 3, v143
	s_mul_i32 s59, s59, 0x90000
	v_and_b32_e32 v2, 0x78, v17
	s_add_u32 s64, s17, s59
	v_ashrrev_i32_e32 v16, 4, v143
	v_lshlrev_b32_e32 v18, 1, v2
	s_addc_u32 s65, s19, s65
	v_lshl_or_b32 v42, v16, 8, v18
	v_mov_b32_e32 v43, v138
	v_lshl_add_u64 v[38:39], s[64:65], 0, v[42:43]
	v_add_co_u32_e32 v6, vcc, s23, v38
	v_lshlrev_b32_e32 v140, 4, v143
	s_nop 0
	v_addc_co_u32_e32 v7, vcc, 0, v39, vcc
	global_load_dwordx4 v[2:5], v42, s[64:65]
	s_nop 0
	global_load_dwordx4 v[6:9], v[6:7], off
	s_nop 0
	global_load_dwordx4 v[10:13], v140, s[10:11]
	v_ashrrev_i32_e32 v155, 6, v143
	v_and_b32_e32 v153, 31, v143
	v_lshlrev_b32_e32 v142, 5, v155
	v_or_b32_e32 v14, v142, v153
	v_ashrrev_i32_e32 v15, 31, v14
	v_bfe_u32 v154, v143, 5, 1
	v_lshlrev_b64 v[14:15], 7, v[14:15]
	v_lshl_add_u64 v[14:15], s[12:13], 0, v[14:15]
	v_lshlrev_b32_e32 v144, 4, v154
	v_mov_b32_e32 v145, v138
	v_lshl_add_u64 v[14:15], v[14:15], 0, v[144:145]
	global_load_dwordx4 v[126:129], v[14:15], off
	global_load_dwordx4 v[122:125], v[14:15], off offset:32
	global_load_dwordx4 v[118:121], v[14:15], off offset:64
	global_load_dwordx4 v[114:117], v[14:15], off offset:96
	v_add_u32_e32 v232, 0x4000, v42
	v_add_u32_e32 v233, 0x6000, v42
	v_add_u32_e32 v234, 0x2000, v140
	global_load_dwordx4 v[220:223], v232, s[64:65]
	global_load_dwordx4 v[224:227], v233, s[64:65]
	global_load_dwordx4 v[228:231], v234, s[10:11]
	v_and_b32_e32 v14, 0xfffff8, v16
	v_lshlrev_b32_e32 v15, 1, v16
	v_lshrrev_b32_e32 v19, 1, v16
	v_and_b32_e32 v21, 3, v16
	v_add_u32_e32 v16, 32, v16
	v_bfe_u32 v20, v17, 5, 2
	v_and_b32_e32 v31, 0x70, v17
	v_and_or_b32 v14, v15, 0, v14
	v_and_b32_e32 v17, 0xfffff8, v16
	v_lshlrev_b32_e32 v16, 1, v16
	v_lshrrev_b32_e32 v14, 1, v14
	v_and_or_b32 v16, v16, 0, v17
	v_bfe_u32 v15, v15, 1, 3
	v_or_b32_e32 v14, v14, v20
	v_lshrrev_b32_e32 v16, 1, v16
	v_lshlrev_b32_e32 v30, 7, v153
	v_lshlrev_b32_e32 v15, 6, v15
	v_and_b32_e32 v18, 48, v18
	v_lshlrev_b32_e32 v14, 9, v14
	v_or_b32_e32 v16, v16, v20
	v_and_b32_e32 v22, 0xffffff80, v140
	v_xor_b32_e32 v23, v140, v143
	v_bitop3_b32 v21, v144, v30, v31 bitop3:0xde
	v_or3_b32 v14, v14, v15, v18
	v_lshlrev_b32_e32 v16, 9, v16
	v_and_or_b32 v19, v23, s22, v22
	v_add_u32_e32 v157, 0, v21
	v_or3_b32 v15, v16, v15, v18
	v_add_u32_e32 v160, 0, v14
	v_add_u32_e32 v158, 0, v19
	v_add_u32_e32 v161, 0, v15
	s_waitcnt vmcnt(3)
	v_or_b32_e32 v26, 64, v144
	v_bitop3_b32 v26, v26, v30, v31 bitop3:0xde
	v_add_u32_e32 v162, 0, v26
	v_or_b32_e32 v32, 0x60, v144
	v_mov_b32_e32 v141, v138
	v_lshl_add_u64 v[40:41], s[10:11], 0, v[140:141]
	v_and_b32_e32 v145, 63, v143
	s_cmp_lg_u32 0, -1
	s_cselect_b32 s11, 0, 0
	s_add_i32 s53, s53, s51
	v_mad_i64_i32 v[146:147], s[12:13], s53, v1, v[140:141]
	s_add_i32 s58, s58, s52
	s_waitcnt vmcnt(6)
	ds_write_b128 v160, v[2:5]
	s_waitcnt vmcnt(5)
	ds_write_b128 v161, v[6:9]
	s_waitcnt vmcnt(4)
	ds_write_b128 v158, v[10:13] offset:32768
	s_waitcnt lgkmcnt(0)
	s_barrier
; #define SLOAD(i, k0) do { const char* vt_ = (const char*)Vh + (size_t)(k0) * 256; const char* kt_ = (const char*)Kh + (size_t)(k0) * 128; \
;     sr_[i].vs0 = *reinterpret_cast<const bf16x8*>(vt_ + voff0); sr_[i].vs1 = *reinterpret_cast<const bf16x8*>(vt_ + 32 * 256 + voff0); \
;     sr_[i].ks0 = *reinterpret_cast<const bf16x8*>(kt_ + koff0); } while (0)
; #define SWRITE(b, i) do { *(bf16x8*)(V_lds + (b) * SHM_V + vst0) = sr_[i].vs0; *(bf16x8*)(V_lds + (b) * SHM_V + vst1) = sr_[i].vs1; \
;     *(bf16x8*)(K_lds + (b) * SHM_K + kst) = sr_[i].ks0; } while (0)
; #define SWAIT() asm volatile("s_waitcnt vmcnt(0)" ::: "memory")
; __device__ __forceinline__ void attn_unit(const bf16* __restrict__ Qb, const bf16* __restrict__ Kh, const bf16* __restrict__ Vh, bf16* __restrict__ Ob, int seq, char* lds) {
;     ...
;     SLOAD(SE, 0); asm volatile("s_waitcnt vmcnt(0)" ::: "memory"); SWRITE(0, SE); __syncthreads();
;     qkt(pA0, pA1, K_lds, qr, r32, hi); softHalf(pA0, l_reg, pa0, pa1);
;     SLOAD(SO, KVBLK);
;     SWAIT(); SWRITE(1, SO); __syncthreads();
	ds_read_b128 v[2:5], v157 offset:32768
	ds_read_b128 v[18:21], v157 offset:36864
	v_or_b32_e32 v6, 32, v144
	v_bitop3_b32 v6, v6, v30, v31 bitop3:0xde
	v_add_u32_e32 v159, 0, v6
	ds_read_b128 v[22:25], v159 offset:32768
	ds_read_b128 v[26:29], v159 offset:36864
	s_waitcnt lgkmcnt(3)
	v_mfma_f32_32x32x16_bf16 v[2:17], v[2:5], v[126:129], 0
	v_bitop3_b32 v30, v32, v30, v31 bitop3:0xde
	v_add_u32_e32 v163, 0, v30
	ds_read_b128 v[30:33], v162 offset:36864
	ds_read_b128 v[34:37], v163 offset:36864
	s_mov_b32 s10, -1
	v_mad_i64_i32 v[148:149], s[12:13], s58, v152, v[42:43]
	s_waitcnt lgkmcnt(3)
	v_mfma_f32_32x32x16_bf16 v[2:17], v[22:25], v[122:125], v[2:17]
	ds_read_b128 v[22:25], v162 offset:32768
	v_mov_b32_e32 v42, v138
	v_mov_b32_e32 v57, v138
	v_mov_b32_e32 v58, v138
	v_mov_b32_e32 v59, v138
	v_mov_b32_e32 v60, v138
	v_mov_b32_e32 v61, v138
	s_waitcnt lgkmcnt(0)
	v_mfma_f32_32x32x16_bf16 v[2:17], v[22:25], v[118:121], v[2:17]
	ds_read_b128 v[22:25], v163 offset:32768
	v_mov_b32_e32 v62, v138
	v_mov_b32_e32 v63, v138
	v_mov_b32_e32 v64, v138
	v_mov_b32_e32 v65, v138
	s_waitcnt lgkmcnt(0)
	v_mfma_f32_32x32x16_bf16 v[2:17], v[22:25], v[114:117], v[2:17]
	v_mfma_f32_32x32x16_bf16 v[66:81], v[18:21], v[126:129], 0
	s_nop 10
	v_exp_f32_e32 v44, v2
	v_add_co_u32_e32 v2, vcc, s34, v38
	v_exp_f32_e32 v45, v3
	s_nop 0
	v_addc_co_u32_e32 v3, vcc, 0, v39, vcc
	v_exp_f32_e32 v46, v4
	v_add_co_u32_e32 v4, vcc, s35, v38
	v_exp_f32_e32 v47, v5
	s_nop 0
	v_addc_co_u32_e32 v5, vcc, 0, v39, vcc
	v_exp_f32_e32 v48, v6
	v_exp_f32_e32 v49, v7
	v_exp_f32_e32 v50, v8
	v_exp_f32_e32 v51, v9
	v_exp_f32_e32 v52, v10
	v_exp_f32_e32 v11, v11
	v_exp_f32_e32 v53, v12
	v_exp_f32_e32 v54, v13
	v_exp_f32_e32 v55, v14
	v_exp_f32_e32 v56, v15
	v_exp_f32_e32 v16, v16
	v_exp_f32_e32 v17, v17
	v_cvt_pk_bf16_f32 v134, v44, v45
	v_cvt_pk_bf16_f32 v135, v46, v47
	v_cvt_pk_bf16_f32 v136, v48, v49
	v_cvt_pk_bf16_f32 v137, v50, v51
	v_cvt_pk_bf16_f32 v130, v52, v11
	v_cvt_pk_bf16_f32 v131, v53, v54
	v_cvt_pk_bf16_f32 v132, v55, v56
	v_cvt_pk_bf16_f32 v133, v16, v17
	v_add_co_u32_e32 v2, vcc, s23, v40
	v_mfma_f32_32x32x16_bf16 v[66:81], v[26:29], v[122:125], v[66:81]
	s_nop 0
	v_addc_co_u32_e32 v3, vcc, 0, v41, vcc
	v_lshlrev_b32_e32 v18, 1, v143
	v_lshlrev_b32_e32 v19, 3, v145
	v_and_b32_e32 v20, 0xc0, v140
	v_and_b32_e32 v18, 32, v18
	v_and_or_b32 v20, v19, 24, v20
	v_and_b32_e32 v19, 0x100, v19
	v_or3_b32 v18, v20, v18, v19
	v_add_u32_e32 v156, s11, v18
	s_addk_i32 s11, 0x4000
	v_add_u32_e32 v141, s11, v18
	v_add_f32_e32 v18, 0, v44
	v_mfma_f32_32x32x16_bf16 v[66:81], v[30:33], v[118:121], v[66:81]
	v_add_f32_e32 v18, v45, v18
	v_add_f32_e32 v18, v46, v18
	v_add_f32_e32 v18, v47, v18
	v_add_f32_e32 v18, v48, v18
	v_add_f32_e32 v18, v49, v18
	v_add_f32_e32 v18, v50, v18
	v_add_f32_e32 v18, v51, v18
	v_add_f32_e32 v18, v52, v18
	v_mfma_f32_32x32x16_bf16 v[66:81], v[34:37], v[114:117], v[66:81]
	v_add_f32_e32 v11, v11, v18
	v_add_f32_e32 v11, v53, v11
	v_add_f32_e32 v11, v54, v11
	v_add_f32_e32 v11, v55, v11
	v_add_f32_e32 v11, v56, v11
	s_waitcnt vmcnt(0)
	v_add_f32_e32 v11, v16, v11
	v_add_f32_e32 v11, v17, v11
	v_mov_b32_e32 v2, v138
	v_mov_b32_e32 v3, v138
	v_mov_b32_e32 v4, v138
	v_mov_b32_e32 v5, v138
	v_mov_b32_e32 v6, v138
	v_mov_b32_e32 v7, v138
	v_mov_b32_e32 v8, v138
	v_mov_b32_e32 v9, v138
	v_mov_b32_e32 v10, v138
	v_add_f32_e32 v139, 0, v11
	s_waitcnt vmcnt(2)
	ds_write_b128 v160, v[220:223] offset:16384
	s_waitcnt vmcnt(1)
	ds_write_b128 v161, v[224:227] offset:16384
	s_waitcnt vmcnt(0)
	ds_write_b128 v158, v[228:231] offset:40960
	v_mov_b32_e32 v11, v138
	v_mov_b32_e32 v12, v138
	v_mov_b32_e32 v13, v138
	v_mov_b32_e32 v14, v138
	v_mov_b32_e32 v15, v138
	v_mov_b32_e32 v16, v138
	v_mov_b32_e32 v17, v138
	v_mov_b32_e32 v18, v138
	v_mov_b32_e32 v19, v138
	v_mov_b32_e32 v20, v138
	v_mov_b32_e32 v21, v138
	v_mov_b32_e32 v22, v138
	v_mov_b32_e32 v23, v138
	v_mov_b32_e32 v24, v138
	v_mov_b32_e32 v25, v138
	v_mov_b32_e32 v26, v138
	v_mov_b32_e32 v27, v138
	v_mov_b32_e32 v28, v138
	v_mov_b32_e32 v29, v138
	v_mov_b32_e32 v30, v138
	v_mov_b32_e32 v31, v138
	v_mov_b32_e32 v32, v138
	v_mov_b32_e32 v33, v138
	v_mov_b32_e32 v34, v138
	v_mov_b32_e32 v35, v138
	v_mov_b32_e32 v36, v138
	v_mov_b32_e32 v37, v138
	v_mov_b32_e32 v38, v138
	v_mov_b32_e32 v39, v138
	v_mov_b32_e32 v40, v138
	v_mov_b32_e32 v41, v138
	v_mov_b32_e32 v44, v138
	v_mov_b32_e32 v45, v138
	v_mov_b32_e32 v46, v138
	v_mov_b32_e32 v47, v138
	v_mov_b32_e32 v48, v138
	v_mov_b32_e32 v49, v138
	v_mov_b32_e32 v50, v138
	v_mov_b32_e32 v51, v138
	v_mov_b32_e32 v52, v138
	v_mov_b32_e32 v53, v138
	v_mov_b32_e32 v54, v138
	v_mov_b32_e32 v55, v138
	v_mov_b32_e32 v56, v138
	s_waitcnt lgkmcnt(0)
	s_barrier
